# GEMM K-loops of the multi-unit phases (P1, P4, P10): first iteration peeled, first MFMA of each chain takes inline 0 as C - the 128 accumulator-zeroing v_mov per unit are gone; on top of all30
# speedup vs baseline: 1.0111x; 1.0067x over previous
; template <class Epi, class Sched, bool ALIGN_EPI = false, bool SP2 = false>
; __device__ __forceinline__ void gemm_phase(PG8_LAS unsigned char* lds, const Gemm g, const Sched& S, const Epi& E, const int wid) {
;     ...
;         const bool has_next = S.next(ui + 1, nxt);
;         const char* nA = has_next ? (const char*)g.A + (size_t)nxt.pm * tstep : cA; const char* nB = has_next ? (const char*)g.Bt + (size_t)nxt.pn * tstep : cB;
;         for (int t = 0; t < nt; t += 2) {
;             const bool last = (t == nt - 2);
;             const char* a1 = cA + (size_t)(t + 1) * kstep;
;             const char* a2 = last ? nA : cA + (size_t)(t + 2) * kstep; const char* b2 = last ? nB : cB + (size_t)(t + 2) * kstep;
;             const char* a3 = a2 + kstep; const char* b3 = b2 + kstep;
.LBB0_268:
	s_ashr_i32 s15, s14, 31
	s_lshl_b64 s[16:17], s[14:15], 19
	s_add_u32 s16, s80, s16
	s_addc_u32 s17, s81, s17
	s_and_b64 s[18:19], s[4:5], exec
	s_cselect_b32 s15, s17, s23
	s_cselect_b32 s44, s16, s22
	s_ashr_i32 s13, s12, 31
	s_lshl_b64 s[18:19], s[12:13], 19
	s_add_u32 s18, s10, s18
	s_addc_u32 s19, s11, s19
	s_and_b64 s[26:27], s[4:5], exec
	s_cselect_b32 s13, s19, s25
	s_cselect_b32 s45, s18, s24
	s_add_u32 s22, s22, 0x40080
	s_addc_u32 s23, s23, 0
	s_add_u32 s46, s24, 0x100

; template <class Epi, class Sched, bool ALIGN_EPI = false, bool SP2 = false>
; __device__ __forceinline__ void gemm_phase(PG8_LAS unsigned char* lds, const Gemm g, const Sched& S, const Epi& E, const int wid) {
;     ...
; #pragma unroll
;         for (int a = 0; a < 2; ++a)
; #pragma unroll
;             for (int b = 0; b < 2; ++b)
; #pragma unroll
;                 for (int m = 0; m < 4; ++m)
; #pragma unroll
;                     for (int n = 0; n < 2; ++n) acc[a][b][m][n] = (f32x4){0.f, 0.f, 0.f, 0.f};
	s_addc_u32 s47, s25, 0
	s_mov_b32 s48, -2


; #define PG8_STAGE(bufoff, gbase, voff) do { _Pragma("unroll") for (int _i = 0; _i < 2; ++_i) \
;         __builtin_amdgcn_global_load_lds((const unsigned*)((const char*)(gbase) + (voff)[_i]), (PG8_LAS unsigned*)(lds + (bufoff) + ldsw + _i * 8192), 16, 0, 0); } while (0)
; #define PG8_LDA(dst, b, h) do { _Pragma("unroll") for (int m = 0; m < 4; ++m) _Pragma("unroll") for (int k = 0; k < 2; ++k) dst[m][k] = *(const PG8_LAS bf16x8*)(lds + PG8_SA(b, h) + aoff + m * 2048 + k * 1024); } while (0)
; #define PG8_LDB(dst, b, h) do { _Pragma("unroll") for (int n = 0; n < 2; ++n) _Pragma("unroll") for (int k = 0; k < 2; ++k) dst[n][k] = *(const PG8_LAS bf16x8*)(lds + PG8_SB(b, h) + boff + n * 2048 + k * 1024); } while (0)
; #define PG8_MMA(ai, bj, At, Bt) do { __builtin_amdgcn_s_setprio(1); _Pragma("unroll") for (int m = 0; m < 4; ++m) _Pragma("unroll") for (int n = 0; n < 2; ++n) _Pragma("unroll") for (int k = 0; k < 2; ++k) \
;         acc[ai][bj][m][n] = __builtin_amdgcn_mfma_f32_16x16x32_bf16(Bt[n][k], At[m][k], acc[ai][bj][m][n], 0, 0, 0); __builtin_amdgcn_s_setprio(0); } while (0)
; #define PG8_WAIT_V(n) asm volatile("s_waitcnt vmcnt(" #n ")" ::: "memory")
; #define PG8_WAIT_L(n) asm volatile("s_waitcnt lgkmcnt(" #n ")" ::: "memory")
; #define PG8_BAR __builtin_amdgcn_s_barrier()
; #define PG8_SCHED __builtin_amdgcn_sched_barrier(0)
; template <class Epi, class Sched, bool ALIGN_EPI = false, bool SP2 = false>
; __device__ __forceinline__ void gemm_phase(PG8_LAS unsigned char* lds, const Gemm g, const Sched& S, const Epi& E, const int wid) {
;     ...
;             PG8_LDB(B0, 0, 0); PG8_LDB(B1, 0, 1); PG8_SCHED; PG8_LDA(At, 0, 0); PG8_STAGE(PG8_SA(1, 1), a1 + hstep, voffA);
;             PG8_WAIT_V(8); PG8_WAIT_L(0); PG8_BAR; PG8_MMA(0, 0, At, B0); PG8_MMA(0, 1, At, B1); PG8_BAR; PG8_SCHED;
;             PG8_LDA(At, 0, 1); PG8_STAGE(PG8_SB(0, 0), b2, voffB); PG8_STAGE(PG8_SB(0, 1), b2 + hstep, voffB); PG8_STAGE(PG8_SA(0, 0), a2, voffA);
;             PG8_WAIT_V(8); PG8_WAIT_L(0); PG8_BAR; PG8_MMA(1, 0, At, B0); PG8_MMA(1, 1, At, B1); PG8_BAR; PG8_SCHED;
	ds_read_b128 v[144:147], v151
	ds_read_b128 v[154:157], v151 offset:1024
	ds_read_b128 v[158:161], v151 offset:2048
	ds_read_b128 v[162:165], v151 offset:3072
	ds_read_b128 v[166:169], v152
	ds_read_b128 v[170:173], v152 offset:1024
	ds_read_b128 v[174:177], v152 offset:2048
	ds_read_b128 v[178:181], v152 offset:3072
	s_add_u32 s24, s22, 0xfffc0080
	s_addc_u32 s25, s23, -1
	s_cmp_eq_u32 s48, 12
	s_cselect_b32 s27, s15, s25
	s_cselect_b32 s26, s44, s24
	s_cselect_b32 s25, s13, s47
	s_cselect_b32 s24, s45, s46
	v_lshl_add_u64 v[206:207], s[22:23], 0, v[136:137]
	s_add_i32 m0, s21, 0xc000
	ds_read_b128 v[182:185], v153
	ds_read_b128 v[186:189], v153 offset:1024
	ds_read_b128 v[190:193], v153 offset:2048
	ds_read_b128 v[194:197], v153 offset:3072
	ds_read_b128 v[198:201], v153 offset:4096
	ds_read_b128 v[202:205], v153 offset:5120
	ds_read_b128 v[212:215], v153 offset:6144
	ds_read_b128 v[216:219], v153 offset:7168
	global_load_lds_dwordx4 v[206:207], off
	v_lshl_add_u64 v[206:207], s[22:23], 0, v[138:139]
	s_add_i32 m0, s21, 0xe000
	s_nop 0
	global_load_lds_dwordx4 v[206:207], off
	s_waitcnt vmcnt(8)
	s_waitcnt lgkmcnt(0)
	s_barrier
	s_setprio 1
	s_waitcnt lgkmcnt(0)
	v_mfma_f32_16x16x32_bf16 v[124:127], v[144:147], v[182:185], 0
	v_mfma_f32_16x16x32_bf16 v[116:119], v[158:161], v[182:185], 0
	v_mfma_f32_16x16x32_bf16 v[108:111], v[144:147], v[190:193], 0
	v_mfma_f32_16x16x32_bf16 v[100:103], v[158:161], v[190:193], 0
	v_mfma_f32_16x16x32_bf16 v[92:95], v[144:147], v[198:201], 0
	v_mfma_f32_16x16x32_bf16 v[84:87], v[158:161], v[198:201], 0
	v_mfma_f32_16x16x32_bf16 v[76:79], v[144:147], v[212:215], 0
	v_mfma_f32_16x16x32_bf16 v[68:71], v[158:161], v[212:215], 0
	v_mfma_f32_16x16x32_bf16 v[124:127], v[154:157], v[186:189], v[124:127]
	v_mfma_f32_16x16x32_bf16 v[116:119], v[162:165], v[186:189], v[116:119]
	v_mfma_f32_16x16x32_bf16 v[108:111], v[154:157], v[194:197], v[108:111]
	v_mfma_f32_16x16x32_bf16 v[100:103], v[162:165], v[194:197], v[100:103]
	v_mfma_f32_16x16x32_bf16 v[92:95], v[154:157], v[202:205], v[92:95]
	v_mfma_f32_16x16x32_bf16 v[84:87], v[162:165], v[202:205], v[84:87]
	v_mfma_f32_16x16x32_bf16 v[76:79], v[154:157], v[216:219], v[76:79]
	v_mfma_f32_16x16x32_bf16 v[68:71], v[162:165], v[216:219], v[68:71]
	s_setprio 0
	s_setprio 1
	v_mfma_f32_16x16x32_bf16 v[120:123], v[166:169], v[182:185], 0
	v_mfma_f32_16x16x32_bf16 v[112:115], v[174:177], v[182:185], 0
	v_mfma_f32_16x16x32_bf16 v[104:107], v[166:169], v[190:193], 0
	v_mfma_f32_16x16x32_bf16 v[96:99], v[174:177], v[190:193], 0
	v_mfma_f32_16x16x32_bf16 v[88:91], v[166:169], v[198:201], 0
	v_mfma_f32_16x16x32_bf16 v[80:83], v[174:177], v[198:201], 0
	v_mfma_f32_16x16x32_bf16 v[72:75], v[166:169], v[212:215], 0
	v_mfma_f32_16x16x32_bf16 v[64:67], v[174:177], v[212:215], 0
	v_mfma_f32_16x16x32_bf16 v[120:123], v[170:173], v[186:189], v[120:123]
	v_mfma_f32_16x16x32_bf16 v[112:115], v[178:181], v[186:189], v[112:115]
	v_mfma_f32_16x16x32_bf16 v[104:107], v[170:173], v[194:197], v[104:107]
	v_mfma_f32_16x16x32_bf16 v[96:99], v[178:181], v[194:197], v[96:99]
	v_mfma_f32_16x16x32_bf16 v[88:91], v[170:173], v[202:205], v[88:91]
	v_mfma_f32_16x16x32_bf16 v[80:83], v[178:181], v[202:205], v[80:83]
	v_mfma_f32_16x16x32_bf16 v[72:75], v[170:173], v[216:219], v[72:75]
	v_mfma_f32_16x16x32_bf16 v[64:67], v[178:181], v[216:219], v[64:67]
	s_setprio 0
	s_barrier
	s_add_i32 s49, s40, s9
	v_lshl_add_u64 v[206:207], s[24:25], 0, v[132:133]
	s_mov_b32 m0, s49
	ds_read_b128 v[182:185], v153 offset:16384
	ds_read_b128 v[186:189], v153 offset:17408
	ds_read_b128 v[190:193], v153 offset:18432
	ds_read_b128 v[194:197], v153 offset:19456
	ds_read_b128 v[198:201], v153 offset:20480
	ds_read_b128 v[202:205], v153 offset:21504
	ds_read_b128 v[212:215], v153 offset:22528
	ds_read_b128 v[216:219], v153 offset:23552
	global_load_lds_dwordx4 v[206:207], off
	s_add_i32 m0, s49, 0x2000
	s_add_u32 s50, s24, 0x40000
	v_lshl_add_u64 v[220:221], s[24:25], 0, v[128:129]
	s_addc_u32 s51, s25, 0
	s_add_i32 s49, s41, s9
	global_load_lds_dwordx4 v[220:221], off
	v_lshl_add_u64 v[222:223], s[50:51], 0, v[132:133]
	s_mov_b32 m0, s49
	v_lshl_add_u64 v[224:225], s[26:27], 0, v[130:131]
	global_load_lds_dwordx4 v[222:223], off
	v_lshl_add_u64 v[222:223], s[50:51], 0, v[128:129]
	s_add_i32 m0, s49, 0x2000
	s_nop 0
	global_load_lds_dwordx4 v[222:223], off
	v_lshl_add_u64 v[222:223], s[26:27], 0, v[134:135]
	s_mov_b32 m0, s21
	s_nop 0
	global_load_lds_dwordx4 v[222:223], off
	s_mov_b32 m0, s30
	s_nop 0
	global_load_lds_dwordx4 v[224:225], off
	s_waitcnt vmcnt(8)
	s_waitcnt lgkmcnt(0)
	s_barrier
; #define PG8_STAGE(bufoff, gbase, voff) do { _Pragma("unroll") for (int _i = 0; _i < 2; ++_i) \
;         __builtin_amdgcn_global_load_lds((const unsigned*)((const char*)(gbase) + (voff)[_i]), (PG8_LAS unsigned*)(lds + (bufoff) + ldsw + _i * 8192), 16, 0, 0); } while (0)
; #define PG8_LDA(dst, b, h) do { _Pragma("unroll") for (int m = 0; m < 4; ++m) _Pragma("unroll") for (int k = 0; k < 2; ++k) dst[m][k] = *(const PG8_LAS bf16x8*)(lds + PG8_SA(b, h) + aoff + m * 2048 + k * 1024); } while (0)
; #define PG8_LDB(dst, b, h) do { _Pragma("unroll") for (int n = 0; n < 2; ++n) _Pragma("unroll") for (int k = 0; k < 2; ++k) dst[n][k] = *(const PG8_LAS bf16x8*)(lds + PG8_SB(b, h) + boff + n * 2048 + k * 1024); } while (0)
; #define PG8_MMA(ai, bj, At, Bt) do { __builtin_amdgcn_s_setprio(1); _Pragma("unroll") for (int m = 0; m < 4; ++m) _Pragma("unroll") for (int n = 0; n < 2; ++n) _Pragma("unroll") for (int k = 0; k < 2; ++k) \
;         acc[ai][bj][m][n] = __builtin_amdgcn_mfma_f32_16x16x32_bf16(Bt[n][k], At[m][k], acc[ai][bj][m][n], 0, 0, 0); __builtin_amdgcn_s_setprio(0); } while (0)
; #define PG8_WAIT_V(n) asm volatile("s_waitcnt vmcnt(" #n ")" ::: "memory")
; #define PG8_WAIT_L(n) asm volatile("s_waitcnt lgkmcnt(" #n ")" ::: "memory")
; #define PG8_BAR __builtin_amdgcn_s_barrier()
; #define PG8_SCHED __builtin_amdgcn_sched_barrier(0)
; template <class Epi, class Sched, bool ALIGN_EPI = false, bool SP2 = false>
; __device__ __forceinline__ void gemm_phase(PG8_LAS unsigned char* lds, const Gemm g, const Sched& S, const Epi& E, const int wid) {
;     ...
;             PG8_WAIT_V(8); PG8_WAIT_L(0); PG8_BAR; PG8_MMA(1, 0, At, B0); PG8_MMA(1, 1, At, B1); PG8_BAR; PG8_SCHED;
;             PG8_LDB(B0, 1, 0); PG8_LDB(B1, 1, 1); PG8_SCHED; PG8_LDA(At, 1, 0); PG8_STAGE(PG8_SA(0, 1), a2 + hstep, voffA);
;             PG8_WAIT_V(8); PG8_WAIT_L(0); PG8_BAR; PG8_MMA(0, 0, At, B0); PG8_MMA(0, 1, At, B1); PG8_BAR; PG8_SCHED;
	s_setprio 1
	s_waitcnt lgkmcnt(0)
	v_mfma_f32_16x16x32_bf16 v[60:63], v[144:147], v[182:185], 0
	v_mfma_f32_16x16x32_bf16 v[52:55], v[158:161], v[182:185], 0
	v_mfma_f32_16x16x32_bf16 v[44:47], v[144:147], v[190:193], 0
	v_mfma_f32_16x16x32_bf16 v[36:39], v[158:161], v[190:193], 0
	v_mfma_f32_16x16x32_bf16 v[28:31], v[144:147], v[198:201], 0
	v_mfma_f32_16x16x32_bf16 v[20:23], v[158:161], v[198:201], 0
	v_mfma_f32_16x16x32_bf16 v[12:15], v[144:147], v[212:215], 0
	v_mfma_f32_16x16x32_bf16 v[4:7], v[158:161], v[212:215], 0
	v_mfma_f32_16x16x32_bf16 v[60:63], v[154:157], v[186:189], v[60:63]
	v_mfma_f32_16x16x32_bf16 v[52:55], v[162:165], v[186:189], v[52:55]
	v_mfma_f32_16x16x32_bf16 v[44:47], v[154:157], v[194:197], v[44:47]
	v_mfma_f32_16x16x32_bf16 v[36:39], v[162:165], v[194:197], v[36:39]
	v_mfma_f32_16x16x32_bf16 v[28:31], v[154:157], v[202:205], v[28:31]
	v_mfma_f32_16x16x32_bf16 v[20:23], v[162:165], v[202:205], v[20:23]
	v_mfma_f32_16x16x32_bf16 v[12:15], v[154:157], v[216:219], v[12:15]
	v_mfma_f32_16x16x32_bf16 v[4:7], v[162:165], v[216:219], v[4:7]
	s_setprio 0
	s_setprio 1
	v_mfma_f32_16x16x32_bf16 v[56:59], v[166:169], v[182:185], 0
	v_mfma_f32_16x16x32_bf16 v[48:51], v[174:177], v[182:185], 0
	v_mfma_f32_16x16x32_bf16 v[40:43], v[166:169], v[190:193], 0
	v_mfma_f32_16x16x32_bf16 v[32:35], v[174:177], v[190:193], 0
	v_mfma_f32_16x16x32_bf16 v[24:27], v[166:169], v[198:201], 0
	v_mfma_f32_16x16x32_bf16 v[16:19], v[174:177], v[198:201], 0
	v_mfma_f32_16x16x32_bf16 v[8:11], v[166:169], v[212:215], 0
	v_mfma_f32_16x16x32_bf16 v[0:3], v[174:177], v[212:215], 0
	v_mfma_f32_16x16x32_bf16 v[56:59], v[170:173], v[186:189], v[56:59]
	v_mfma_f32_16x16x32_bf16 v[48:51], v[178:181], v[186:189], v[48:51]
	v_mfma_f32_16x16x32_bf16 v[40:43], v[170:173], v[194:197], v[40:43]
	v_mfma_f32_16x16x32_bf16 v[32:35], v[178:181], v[194:197], v[32:35]
	v_mfma_f32_16x16x32_bf16 v[24:27], v[170:173], v[202:205], v[24:27]
	v_mfma_f32_16x16x32_bf16 v[16:19], v[178:181], v[202:205], v[16:19]
	v_mfma_f32_16x16x32_bf16 v[8:11], v[170:173], v[216:219], v[8:11]
	v_mfma_f32_16x16x32_bf16 v[0:3], v[178:181], v[216:219], v[0:3]
	s_setprio 0
	s_barrier
	s_add_i32 s49, 0, 0x18000
	s_add_i32 s50, 0, 0x1c000
	v_add_u32_e32 v162, s49, v149
	v_add_u32_e32 v178, s50, v149
	ds_read_b128 v[144:147], v162
	ds_read_b128 v[154:157], v162 offset:1024
	ds_read_b128 v[158:161], v162 offset:2048
	ds_read_b128 v[162:165], v162 offset:3072
	ds_read_b128 v[166:169], v178
	ds_read_b128 v[170:173], v178 offset:1024
	ds_read_b128 v[174:177], v178 offset:2048
	ds_read_b128 v[178:181], v178 offset:3072
	s_add_u32 s26, s26, 0x40000
	s_addc_u32 s27, s27, 0
	s_mov_b32 m0, s31
	v_lshl_add_u64 v[226:227], s[26:27], 0, v[134:135]
	ds_read_b128 v[182:185], v153 offset:32768
	ds_read_b128 v[186:189], v153 offset:33792
	ds_read_b128 v[190:193], v153 offset:34816
	ds_read_b128 v[194:197], v153 offset:35840
	ds_read_b128 v[198:201], v153 offset:36864
	ds_read_b128 v[202:205], v153 offset:37888
	ds_read_b128 v[212:215], v153 offset:38912
	ds_read_b128 v[216:219], v153 offset:39936
	global_load_lds_dwordx4 v[226:227], off
	v_lshl_add_u64 v[226:227], s[26:27], 0, v[130:131]
	s_mov_b32 m0, s33
	s_nop 0
	global_load_lds_dwordx4 v[226:227], off
	s_waitcnt vmcnt(8)
	s_waitcnt lgkmcnt(0)
	s_barrier
	s_setprio 1
	s_waitcnt lgkmcnt(0)
	v_mfma_f32_16x16x32_bf16 v[124:127], v[144:147], v[182:185], v[124:127]
	v_mfma_f32_16x16x32_bf16 v[116:119], v[158:161], v[182:185], v[116:119]
	v_mfma_f32_16x16x32_bf16 v[108:111], v[144:147], v[190:193], v[108:111]
	v_mfma_f32_16x16x32_bf16 v[100:103], v[158:161], v[190:193], v[100:103]
	v_mfma_f32_16x16x32_bf16 v[92:95], v[144:147], v[198:201], v[92:95]
	v_mfma_f32_16x16x32_bf16 v[84:87], v[158:161], v[198:201], v[84:87]
	v_mfma_f32_16x16x32_bf16 v[76:79], v[144:147], v[212:215], v[76:79]
	v_mfma_f32_16x16x32_bf16 v[68:71], v[158:161], v[212:215], v[68:71]
	v_mfma_f32_16x16x32_bf16 v[124:127], v[154:157], v[186:189], v[124:127]
	v_mfma_f32_16x16x32_bf16 v[116:119], v[162:165], v[186:189], v[116:119]
	v_mfma_f32_16x16x32_bf16 v[108:111], v[154:157], v[194:197], v[108:111]
	v_mfma_f32_16x16x32_bf16 v[100:103], v[162:165], v[194:197], v[100:103]
	v_mfma_f32_16x16x32_bf16 v[92:95], v[154:157], v[202:205], v[92:95]
	v_mfma_f32_16x16x32_bf16 v[84:87], v[162:165], v[202:205], v[84:87]
	v_mfma_f32_16x16x32_bf16 v[76:79], v[154:157], v[216:219], v[76:79]
	v_mfma_f32_16x16x32_bf16 v[68:71], v[162:165], v[216:219], v[68:71]
	s_setprio 0
	s_setprio 1
	v_mfma_f32_16x16x32_bf16 v[120:123], v[166:169], v[182:185], v[120:123]
	v_mfma_f32_16x16x32_bf16 v[112:115], v[174:177], v[182:185], v[112:115]
	v_mfma_f32_16x16x32_bf16 v[104:107], v[166:169], v[190:193], v[104:107]
	v_mfma_f32_16x16x32_bf16 v[96:99], v[174:177], v[190:193], v[96:99]
	v_mfma_f32_16x16x32_bf16 v[88:91], v[166:169], v[198:201], v[88:91]
	v_mfma_f32_16x16x32_bf16 v[80:83], v[174:177], v[198:201], v[80:83]
	v_mfma_f32_16x16x32_bf16 v[72:75], v[166:169], v[212:215], v[72:75]
	v_mfma_f32_16x16x32_bf16 v[64:67], v[174:177], v[212:215], v[64:67]
	v_mfma_f32_16x16x32_bf16 v[120:123], v[170:173], v[186:189], v[120:123]
	v_mfma_f32_16x16x32_bf16 v[112:115], v[178:181], v[186:189], v[112:115]
	v_mfma_f32_16x16x32_bf16 v[104:107], v[170:173], v[194:197], v[104:107]
	v_mfma_f32_16x16x32_bf16 v[96:99], v[178:181], v[194:197], v[96:99]
	v_mfma_f32_16x16x32_bf16 v[88:91], v[170:173], v[202:205], v[88:91]
	v_mfma_f32_16x16x32_bf16 v[80:83], v[178:181], v[202:205], v[80:83]
	v_mfma_f32_16x16x32_bf16 v[72:75], v[170:173], v[216:219], v[72:75]
	v_mfma_f32_16x16x32_bf16 v[64:67], v[178:181], v[216:219], v[64:67]
	s_setprio 0
	s_barrier
; #define PG8_STAGE(bufoff, gbase, voff) do { _Pragma("unroll") for (int _i = 0; _i < 2; ++_i) \
;         __builtin_amdgcn_global_load_lds((const unsigned*)((const char*)(gbase) + (voff)[_i]), (PG8_LAS unsigned*)(lds + (bufoff) + ldsw + _i * 8192), 16, 0, 0); } while (0)
; #define PG8_LDA(dst, b, h) do { _Pragma("unroll") for (int m = 0; m < 4; ++m) _Pragma("unroll") for (int k = 0; k < 2; ++k) dst[m][k] = *(const PG8_LAS bf16x8*)(lds + PG8_SA(b, h) + aoff + m * 2048 + k * 1024); } while (0)
; #define PG8_MMA(ai, bj, At, Bt) do { __builtin_amdgcn_s_setprio(1); _Pragma("unroll") for (int m = 0; m < 4; ++m) _Pragma("unroll") for (int n = 0; n < 2; ++n) _Pragma("unroll") for (int k = 0; k < 2; ++k) \
;         acc[ai][bj][m][n] = __builtin_amdgcn_mfma_f32_16x16x32_bf16(Bt[n][k], At[m][k], acc[ai][bj][m][n], 0, 0, 0); __builtin_amdgcn_s_setprio(0); } while (0)
; #define PG8_WAIT_V(n) asm volatile("s_waitcnt vmcnt(" #n ")" ::: "memory")
; #define PG8_WAIT_L(n) asm volatile("s_waitcnt lgkmcnt(" #n ")" ::: "memory")
; #define PG8_BAR __builtin_amdgcn_s_barrier()
; #define PG8_SCHED __builtin_amdgcn_sched_barrier(0)
; template <class Epi, class Sched, bool ALIGN_EPI = false, bool SP2 = false>
; __device__ __forceinline__ void gemm_phase(PG8_LAS unsigned char* lds, const Gemm g, const Sched& S, const Epi& E, const int wid) {
;     ...
;         for (int t = 0; t < nt; t += 2) {
;     ...
;             PG8_LDA(At, 1, 1); PG8_STAGE(PG8_SB(1, 0), b3, voffB); PG8_STAGE(PG8_SB(1, 1), b3 + hstep, voffB); PG8_STAGE(PG8_SA(1, 0), a3, voffA);
;             PG8_WAIT_V(8); PG8_WAIT_L(0); PG8_BAR; PG8_MMA(1, 0, At, B0); PG8_MMA(1, 1, At, B1); PG8_BAR; PG8_SCHED;
	s_add_i32 s26, s49, s9
	v_lshl_add_u64 v[206:207], v[206:207], 0, s[6:7]
	s_mov_b32 m0, s26
	ds_read_b128 v[182:185], v153 offset:49152
	ds_read_b128 v[186:189], v153 offset:50176
	ds_read_b128 v[190:193], v153 offset:51200
	ds_read_b128 v[194:197], v153 offset:52224
	ds_read_b128 v[198:201], v153 offset:53248
	ds_read_b128 v[202:205], v153 offset:54272
	ds_read_b128 v[212:215], v153 offset:55296
	ds_read_b128 v[216:219], v153 offset:56320
	global_load_lds_dwordx4 v[206:207], off
	s_add_i32 m0, s26, 0x2000
	s_add_u32 s24, s24, 0x40080
	v_lshl_add_u64 v[206:207], v[220:221], 0, s[6:7]
	s_addc_u32 s25, s25, 0
	s_add_i32 s26, s50, s9
	global_load_lds_dwordx4 v[206:207], off
	v_lshl_add_u64 v[206:207], s[24:25], 0, v[132:133]
	s_mov_b32 m0, s26
	s_nop 0
	global_load_lds_dwordx4 v[206:207], off
	v_lshl_add_u64 v[206:207], s[24:25], 0, v[128:129]
	s_add_i32 m0, s26, 0x2000
	s_nop 0
	global_load_lds_dwordx4 v[206:207], off
	v_lshl_add_u64 v[206:207], v[222:223], 0, s[6:7]
	s_mov_b32 m0, s38
	s_nop 0
	global_load_lds_dwordx4 v[206:207], off
	v_lshl_add_u64 v[206:207], v[224:225], 0, s[6:7]
	s_mov_b32 m0, s39
	s_nop 0
	global_load_lds_dwordx4 v[206:207], off
	s_waitcnt vmcnt(8)
	s_waitcnt lgkmcnt(0)
	s_barrier
	s_setprio 1
	s_waitcnt lgkmcnt(0)
	v_mfma_f32_16x16x32_bf16 v[60:63], v[144:147], v[182:185], v[60:63]
	v_mfma_f32_16x16x32_bf16 v[52:55], v[158:161], v[182:185], v[52:55]
	v_mfma_f32_16x16x32_bf16 v[44:47], v[144:147], v[190:193], v[44:47]
	v_mfma_f32_16x16x32_bf16 v[36:39], v[158:161], v[190:193], v[36:39]
	v_mfma_f32_16x16x32_bf16 v[28:31], v[144:147], v[198:201], v[28:31]
	v_mfma_f32_16x16x32_bf16 v[20:23], v[158:161], v[198:201], v[20:23]
	v_mfma_f32_16x16x32_bf16 v[12:15], v[144:147], v[212:215], v[12:15]
	v_mfma_f32_16x16x32_bf16 v[4:7], v[158:161], v[212:215], v[4:7]
	v_mfma_f32_16x16x32_bf16 v[60:63], v[154:157], v[186:189], v[60:63]
	v_mfma_f32_16x16x32_bf16 v[52:55], v[162:165], v[186:189], v[52:55]
	v_mfma_f32_16x16x32_bf16 v[44:47], v[154:157], v[194:197], v[44:47]
	v_mfma_f32_16x16x32_bf16 v[36:39], v[162:165], v[194:197], v[36:39]
	v_mfma_f32_16x16x32_bf16 v[28:31], v[154:157], v[202:205], v[28:31]
	v_mfma_f32_16x16x32_bf16 v[20:23], v[162:165], v[202:205], v[20:23]
	v_mfma_f32_16x16x32_bf16 v[12:15], v[154:157], v[216:219], v[12:15]
	v_mfma_f32_16x16x32_bf16 v[4:7], v[162:165], v[216:219], v[4:7]
	s_setprio 0
	s_setprio 1
	v_mfma_f32_16x16x32_bf16 v[56:59], v[166:169], v[182:185], v[56:59]
	v_mfma_f32_16x16x32_bf16 v[48:51], v[174:177], v[182:185], v[48:51]
	v_mfma_f32_16x16x32_bf16 v[40:43], v[166:169], v[190:193], v[40:43]
	v_mfma_f32_16x16x32_bf16 v[32:35], v[174:177], v[190:193], v[32:35]
	v_mfma_f32_16x16x32_bf16 v[24:27], v[166:169], v[198:201], v[24:27]
	v_mfma_f32_16x16x32_bf16 v[16:19], v[174:177], v[198:201], v[16:19]
	v_mfma_f32_16x16x32_bf16 v[8:11], v[166:169], v[212:215], v[8:11]
	v_mfma_f32_16x16x32_bf16 v[0:3], v[174:177], v[212:215], v[0:3]
	v_mfma_f32_16x16x32_bf16 v[56:59], v[170:173], v[186:189], v[56:59]
	v_mfma_f32_16x16x32_bf16 v[48:51], v[178:181], v[186:189], v[48:51]
	v_mfma_f32_16x16x32_bf16 v[40:43], v[170:173], v[194:197], v[40:43]
	v_mfma_f32_16x16x32_bf16 v[32:35], v[178:181], v[194:197], v[32:35]
	v_mfma_f32_16x16x32_bf16 v[24:27], v[170:173], v[202:205], v[24:27]
	v_mfma_f32_16x16x32_bf16 v[16:19], v[178:181], v[202:205], v[16:19]
	v_mfma_f32_16x16x32_bf16 v[8:11], v[170:173], v[216:219], v[8:11]
	v_mfma_f32_16x16x32_bf16 v[0:3], v[178:181], v[216:219], v[0:3]
	s_setprio 0
	s_barrier
	s_add_i32 s48, s48, 2
	s_add_u32 s22, s22, 0x100
	s_addc_u32 s23, s23, 0
	s_add_u32 s46, s46, 0x100
	s_addc_u32 s47, s47, 0
	s_cmp_gt_u32 s48, 13
	s_cbranch_scc0 .LBB0_269
	s_branch .Lkp_exit_0

; #define PG8_BAR __builtin_amdgcn_s_barrier()
; template <class Epi, class Sched, bool ALIGN_EPI = false, bool SP2 = false>
; __device__ __forceinline__ void gemm_phase(PG8_LAS unsigned char* lds, const Gemm g, const Sched& S, const Epi& E, const int wid) {
;     ...
;         if constexpr (ALIGN_EPI) { if (wr == 0) PG8_BAR; }
.Lkp_exit_0:
	s_and_b64 vcc, exec, s[2:3]
	s_cbranch_vccz .LBB0_272
	s_barrier

; template <class Epi, class Sched, bool ALIGN_EPI = false, bool SP2 = false>
; __device__ __forceinline__ void gemm_phase(PG8_LAS unsigned char* lds, const Gemm g, const Sched& S, const Epi& E, const int wid) {
;     ...
;         const bool has_next = S.next(ui + 1, nxt);
;         const char* nA = has_next ? (const char*)g.A + (size_t)nxt.pm * tstep : cA; const char* nB = has_next ? (const char*)g.Bt + (size_t)nxt.pn * tstep : cB;
;         for (int t = 0; t < nt; t += 2) {
;             const bool last = (t == nt - 2);
;             const char* a1 = cA + (size_t)(t + 1) * kstep;
;             const char* a2 = last ? nA : cA + (size_t)(t + 2) * kstep; const char* b2 = last ? nB : cB + (size_t)(t + 2) * kstep;
;             const char* a3 = a2 + kstep; const char* b3 = b2 + kstep;
.LBB0_881:
	s_ashr_i32 s13, s12, 31
	s_lshl_b64 s[14:15], s[12:13], 19
	s_add_u32 s14, s80, s14
	s_addc_u32 s15, s81, s15
	s_and_b64 s[18:19], s[4:5], exec
	s_cselect_b32 s13, s15, s21
	s_cselect_b32 s43, s14, s20
	s_ashr_i32 s9, s8, 31
	s_lshl_b64 s[18:19], s[8:9], 19
	s_add_u32 s18, s10, s18
	s_addc_u32 s19, s11, s19
	s_and_b64 s[24:25], s[4:5], exec
	s_cselect_b32 s9, s19, s23
	s_cselect_b32 s44, s18, s22
	s_add_u32 s20, s20, 0x40080
	s_addc_u32 s21, s21, 0
	s_add_u32 s45, s22, 0x100

; template <class Epi, class Sched, bool ALIGN_EPI = false, bool SP2 = false>
; __device__ __forceinline__ void gemm_phase(PG8_LAS unsigned char* lds, const Gemm g, const Sched& S, const Epi& E, const int wid) {
;     ...
; #pragma unroll
;         for (int a = 0; a < 2; ++a)
; #pragma unroll
;             for (int b = 0; b < 2; ++b)
; #pragma unroll
;                 for (int m = 0; m < 4; ++m)
; #pragma unroll
;                     for (int n = 0; n < 2; ++n) acc[a][b][m][n] = (f32x4){0.f, 0.f, 0.f, 0.f};
	s_addc_u32 s46, s23, 0
	s_mov_b32 s47, -2


; #define PG8_STAGE(bufoff, gbase, voff) do { _Pragma("unroll") for (int _i = 0; _i < 2; ++_i) \
;         __builtin_amdgcn_global_load_lds((const unsigned*)((const char*)(gbase) + (voff)[_i]), (PG8_LAS unsigned*)(lds + (bufoff) + ldsw + _i * 8192), 16, 0, 0); } while (0)
; #define PG8_LDA(dst, b, h) do { _Pragma("unroll") for (int m = 0; m < 4; ++m) _Pragma("unroll") for (int k = 0; k < 2; ++k) dst[m][k] = *(const PG8_LAS bf16x8*)(lds + PG8_SA(b, h) + aoff + m * 2048 + k * 1024); } while (0)
; #define PG8_LDB(dst, b, h) do { _Pragma("unroll") for (int n = 0; n < 2; ++n) _Pragma("unroll") for (int k = 0; k < 2; ++k) dst[n][k] = *(const PG8_LAS bf16x8*)(lds + PG8_SB(b, h) + boff + n * 2048 + k * 1024); } while (0)
; #define PG8_MMA(ai, bj, At, Bt) do { __builtin_amdgcn_s_setprio(1); _Pragma("unroll") for (int m = 0; m < 4; ++m) _Pragma("unroll") for (int n = 0; n < 2; ++n) _Pragma("unroll") for (int k = 0; k < 2; ++k) \
;         acc[ai][bj][m][n] = __builtin_amdgcn_mfma_f32_16x16x32_bf16(Bt[n][k], At[m][k], acc[ai][bj][m][n], 0, 0, 0); __builtin_amdgcn_s_setprio(0); } while (0)
; #define PG8_WAIT_V(n) asm volatile("s_waitcnt vmcnt(" #n ")" ::: "memory")
; #define PG8_WAIT_L(n) asm volatile("s_waitcnt lgkmcnt(" #n ")" ::: "memory")
; #define PG8_BAR __builtin_amdgcn_s_barrier()
; #define PG8_SCHED __builtin_amdgcn_sched_barrier(0)
; template <class Epi, class Sched, bool ALIGN_EPI = false, bool SP2 = false>
; __device__ __forceinline__ void gemm_phase(PG8_LAS unsigned char* lds, const Gemm g, const Sched& S, const Epi& E, const int wid) {
;     ...
;             PG8_LDB(B0, 0, 0); PG8_LDB(B1, 0, 1); PG8_SCHED; PG8_LDA(At, 0, 0); PG8_STAGE(PG8_SA(1, 1), a1 + hstep, voffA);
;             PG8_WAIT_V(8); PG8_WAIT_L(0); PG8_BAR; PG8_MMA(0, 0, At, B0); PG8_MMA(0, 1, At, B1); PG8_BAR; PG8_SCHED;
;             PG8_LDA(At, 0, 1); PG8_STAGE(PG8_SB(0, 0), b2, voffB); PG8_STAGE(PG8_SB(0, 1), b2 + hstep, voffB); PG8_STAGE(PG8_SA(0, 0), a2, voffA);
;             PG8_WAIT_V(8); PG8_WAIT_L(0); PG8_BAR; PG8_MMA(1, 0, At, B0); PG8_MMA(1, 1, At, B1); PG8_BAR; PG8_SCHED;
	ds_read_b128 v[152:155], v149
	ds_read_b128 v[156:159], v149 offset:1024
	ds_read_b128 v[160:163], v149 offset:2048
	ds_read_b128 v[164:167], v149 offset:3072
	ds_read_b128 v[168:171], v150
	ds_read_b128 v[172:175], v150 offset:1024
	ds_read_b128 v[176:179], v150 offset:2048
	ds_read_b128 v[180:183], v150 offset:3072
	s_add_u32 s22, s20, 0xfffc0080
	s_addc_u32 s23, s21, -1
	s_cmp_eq_u32 s47, 12
	s_cselect_b32 s25, s13, s23
	s_cselect_b32 s24, s43, s22
	s_cselect_b32 s23, s9, s46
	s_cselect_b32 s22, s44, s45
	v_lshl_add_u64 v[144:145], s[20:21], 0, v[136:137]
	s_add_i32 m0, s17, 0xc000
	ds_read_b128 v[184:187], v151
	ds_read_b128 v[188:191], v151 offset:1024
	ds_read_b128 v[192:195], v151 offset:2048
	ds_read_b128 v[196:199], v151 offset:3072
	ds_read_b128 v[200:203], v151 offset:4096
	ds_read_b128 v[204:207], v151 offset:5120
	ds_read_b128 v[212:215], v151 offset:6144
	ds_read_b128 v[216:219], v151 offset:7168
	global_load_lds_dwordx4 v[144:145], off
	v_lshl_add_u64 v[144:145], s[20:21], 0, v[138:139]
	s_add_i32 m0, s17, 0xe000
	s_nop 0
	global_load_lds_dwordx4 v[144:145], off
	s_waitcnt vmcnt(8)
	s_waitcnt lgkmcnt(0)
	s_barrier
	s_setprio 1
	s_waitcnt lgkmcnt(0)
	v_mfma_f32_16x16x32_bf16 v[124:127], v[152:155], v[184:187], 0
	v_mfma_f32_16x16x32_bf16 v[120:123], v[160:163], v[184:187], 0
	v_mfma_f32_16x16x32_bf16 v[116:119], v[152:155], v[192:195], 0
	v_mfma_f32_16x16x32_bf16 v[108:111], v[160:163], v[192:195], 0
	v_mfma_f32_16x16x32_bf16 v[100:103], v[152:155], v[200:203], 0
	v_mfma_f32_16x16x32_bf16 v[92:95], v[160:163], v[200:203], 0
	v_mfma_f32_16x16x32_bf16 v[84:87], v[152:155], v[212:215], 0
	v_mfma_f32_16x16x32_bf16 v[76:79], v[160:163], v[212:215], 0
	v_mfma_f32_16x16x32_bf16 v[124:127], v[156:159], v[188:191], v[124:127]
	v_mfma_f32_16x16x32_bf16 v[120:123], v[164:167], v[188:191], v[120:123]
	v_mfma_f32_16x16x32_bf16 v[116:119], v[156:159], v[196:199], v[116:119]
	v_mfma_f32_16x16x32_bf16 v[108:111], v[164:167], v[196:199], v[108:111]
	v_mfma_f32_16x16x32_bf16 v[100:103], v[156:159], v[204:207], v[100:103]
	v_mfma_f32_16x16x32_bf16 v[92:95], v[164:167], v[204:207], v[92:95]
	v_mfma_f32_16x16x32_bf16 v[84:87], v[156:159], v[216:219], v[84:87]
	v_mfma_f32_16x16x32_bf16 v[76:79], v[164:167], v[216:219], v[76:79]
	s_setprio 0
	s_setprio 1
	v_mfma_f32_16x16x32_bf16 v[112:115], v[168:171], v[184:187], 0
	v_mfma_f32_16x16x32_bf16 v[104:107], v[176:179], v[184:187], 0
	v_mfma_f32_16x16x32_bf16 v[96:99], v[168:171], v[192:195], 0
	v_mfma_f32_16x16x32_bf16 v[88:91], v[176:179], v[192:195], 0
	v_mfma_f32_16x16x32_bf16 v[80:83], v[168:171], v[200:203], 0
	v_mfma_f32_16x16x32_bf16 v[72:75], v[176:179], v[200:203], 0
	v_mfma_f32_16x16x32_bf16 v[68:71], v[168:171], v[212:215], 0
	v_mfma_f32_16x16x32_bf16 v[64:67], v[176:179], v[212:215], 0
	v_mfma_f32_16x16x32_bf16 v[112:115], v[172:175], v[188:191], v[112:115]
	v_mfma_f32_16x16x32_bf16 v[104:107], v[180:183], v[188:191], v[104:107]
	v_mfma_f32_16x16x32_bf16 v[96:99], v[172:175], v[196:199], v[96:99]
	v_mfma_f32_16x16x32_bf16 v[88:91], v[180:183], v[196:199], v[88:91]
	v_mfma_f32_16x16x32_bf16 v[80:83], v[172:175], v[204:207], v[80:83]
	v_mfma_f32_16x16x32_bf16 v[72:75], v[180:183], v[204:207], v[72:75]
	v_mfma_f32_16x16x32_bf16 v[68:71], v[172:175], v[216:219], v[68:71]
	v_mfma_f32_16x16x32_bf16 v[64:67], v[180:183], v[216:219], v[64:67]
	s_setprio 0
	s_barrier
	s_add_i32 s48, s39, s26
	v_lshl_add_u64 v[144:145], s[22:23], 0, v[132:133]
	s_mov_b32 m0, s48
	ds_read_b128 v[184:187], v151 offset:16384
	ds_read_b128 v[188:191], v151 offset:17408
	ds_read_b128 v[192:195], v151 offset:18432
	ds_read_b128 v[196:199], v151 offset:19456
	ds_read_b128 v[200:203], v151 offset:20480
	ds_read_b128 v[204:207], v151 offset:21504
	ds_read_b128 v[212:215], v151 offset:22528
	ds_read_b128 v[216:219], v151 offset:23552
	global_load_lds_dwordx4 v[144:145], off
	s_add_i32 m0, s48, 0x2000
	s_add_u32 s48, s22, 0x40000
	v_lshl_add_u64 v[220:221], s[22:23], 0, v[128:129]
	s_addc_u32 s49, s23, 0
	s_add_i32 s50, s40, s26
	global_load_lds_dwordx4 v[220:221], off
	v_lshl_add_u64 v[222:223], s[48:49], 0, v[132:133]
	s_mov_b32 m0, s50
	v_lshl_add_u64 v[224:225], s[24:25], 0, v[130:131]
	global_load_lds_dwordx4 v[222:223], off
	v_lshl_add_u64 v[222:223], s[48:49], 0, v[128:129]
	s_add_i32 m0, s50, 0x2000
	s_nop 0
	global_load_lds_dwordx4 v[222:223], off
	v_lshl_add_u64 v[222:223], s[24:25], 0, v[134:135]
	s_mov_b32 m0, s17
	s_nop 0
	global_load_lds_dwordx4 v[222:223], off
	s_mov_b32 m0, s29
	s_nop 0
	global_load_lds_dwordx4 v[224:225], off
	s_waitcnt vmcnt(8)
	s_waitcnt lgkmcnt(0)
	s_barrier
; #define PG8_STAGE(bufoff, gbase, voff) do { _Pragma("unroll") for (int _i = 0; _i < 2; ++_i) \
;         __builtin_amdgcn_global_load_lds((const unsigned*)((const char*)(gbase) + (voff)[_i]), (PG8_LAS unsigned*)(lds + (bufoff) + ldsw + _i * 8192), 16, 0, 0); } while (0)
; #define PG8_LDA(dst, b, h) do { _Pragma("unroll") for (int m = 0; m < 4; ++m) _Pragma("unroll") for (int k = 0; k < 2; ++k) dst[m][k] = *(const PG8_LAS bf16x8*)(lds + PG8_SA(b, h) + aoff + m * 2048 + k * 1024); } while (0)
; #define PG8_LDB(dst, b, h) do { _Pragma("unroll") for (int n = 0; n < 2; ++n) _Pragma("unroll") for (int k = 0; k < 2; ++k) dst[n][k] = *(const PG8_LAS bf16x8*)(lds + PG8_SB(b, h) + boff + n * 2048 + k * 1024); } while (0)
; #define PG8_MMA(ai, bj, At, Bt) do { __builtin_amdgcn_s_setprio(1); _Pragma("unroll") for (int m = 0; m < 4; ++m) _Pragma("unroll") for (int n = 0; n < 2; ++n) _Pragma("unroll") for (int k = 0; k < 2; ++k) \
;         acc[ai][bj][m][n] = __builtin_amdgcn_mfma_f32_16x16x32_bf16(Bt[n][k], At[m][k], acc[ai][bj][m][n], 0, 0, 0); __builtin_amdgcn_s_setprio(0); } while (0)
; #define PG8_WAIT_V(n) asm volatile("s_waitcnt vmcnt(" #n ")" ::: "memory")
; #define PG8_WAIT_L(n) asm volatile("s_waitcnt lgkmcnt(" #n ")" ::: "memory")
; #define PG8_BAR __builtin_amdgcn_s_barrier()
; #define PG8_SCHED __builtin_amdgcn_sched_barrier(0)
; template <class Epi, class Sched, bool ALIGN_EPI = false, bool SP2 = false>
; __device__ __forceinline__ void gemm_phase(PG8_LAS unsigned char* lds, const Gemm g, const Sched& S, const Epi& E, const int wid) {
;     ...
;             PG8_WAIT_V(8); PG8_WAIT_L(0); PG8_BAR; PG8_MMA(1, 0, At, B0); PG8_MMA(1, 1, At, B1); PG8_BAR; PG8_SCHED;
;             PG8_LDB(B0, 1, 0); PG8_LDB(B1, 1, 1); PG8_SCHED; PG8_LDA(At, 1, 0); PG8_STAGE(PG8_SA(0, 1), a2 + hstep, voffA);
;             PG8_WAIT_V(8); PG8_WAIT_L(0); PG8_BAR; PG8_MMA(0, 0, At, B0); PG8_MMA(0, 1, At, B1); PG8_BAR; PG8_SCHED;
	s_setprio 1
	s_waitcnt lgkmcnt(0)
	v_mfma_f32_16x16x32_bf16 v[60:63], v[152:155], v[184:187], 0
	v_mfma_f32_16x16x32_bf16 v[56:59], v[160:163], v[184:187], 0
	v_mfma_f32_16x16x32_bf16 v[52:55], v[152:155], v[192:195], 0
	v_mfma_f32_16x16x32_bf16 v[44:47], v[160:163], v[192:195], 0
	v_mfma_f32_16x16x32_bf16 v[36:39], v[152:155], v[200:203], 0
	v_mfma_f32_16x16x32_bf16 v[28:31], v[160:163], v[200:203], 0
	v_mfma_f32_16x16x32_bf16 v[20:23], v[152:155], v[212:215], 0
	v_mfma_f32_16x16x32_bf16 v[12:15], v[160:163], v[212:215], 0
	v_mfma_f32_16x16x32_bf16 v[60:63], v[156:159], v[188:191], v[60:63]
	v_mfma_f32_16x16x32_bf16 v[56:59], v[164:167], v[188:191], v[56:59]
	v_mfma_f32_16x16x32_bf16 v[52:55], v[156:159], v[196:199], v[52:55]
	v_mfma_f32_16x16x32_bf16 v[44:47], v[164:167], v[196:199], v[44:47]
	v_mfma_f32_16x16x32_bf16 v[36:39], v[156:159], v[204:207], v[36:39]
	v_mfma_f32_16x16x32_bf16 v[28:31], v[164:167], v[204:207], v[28:31]
	v_mfma_f32_16x16x32_bf16 v[20:23], v[156:159], v[216:219], v[20:23]
	v_mfma_f32_16x16x32_bf16 v[12:15], v[164:167], v[216:219], v[12:15]
	s_setprio 0
	s_setprio 1
	v_mfma_f32_16x16x32_bf16 v[48:51], v[168:171], v[184:187], 0
	v_mfma_f32_16x16x32_bf16 v[40:43], v[176:179], v[184:187], 0
	v_mfma_f32_16x16x32_bf16 v[32:35], v[168:171], v[192:195], 0
	v_mfma_f32_16x16x32_bf16 v[24:27], v[176:179], v[192:195], 0
	v_mfma_f32_16x16x32_bf16 v[16:19], v[168:171], v[200:203], 0
	v_mfma_f32_16x16x32_bf16 v[8:11], v[176:179], v[200:203], 0
	v_mfma_f32_16x16x32_bf16 v[4:7], v[168:171], v[212:215], 0
	v_mfma_f32_16x16x32_bf16 v[0:3], v[176:179], v[212:215], 0
	v_mfma_f32_16x16x32_bf16 v[48:51], v[172:175], v[188:191], v[48:51]
	v_mfma_f32_16x16x32_bf16 v[40:43], v[180:183], v[188:191], v[40:43]
	v_mfma_f32_16x16x32_bf16 v[32:35], v[172:175], v[196:199], v[32:35]
	v_mfma_f32_16x16x32_bf16 v[24:27], v[180:183], v[196:199], v[24:27]
	v_mfma_f32_16x16x32_bf16 v[16:19], v[172:175], v[204:207], v[16:19]
	v_mfma_f32_16x16x32_bf16 v[8:11], v[180:183], v[204:207], v[8:11]
	v_mfma_f32_16x16x32_bf16 v[4:7], v[172:175], v[216:219], v[4:7]
	v_mfma_f32_16x16x32_bf16 v[0:3], v[180:183], v[216:219], v[0:3]
	s_setprio 0
	s_barrier
	s_add_i32 s48, 0, 0x18000
	s_add_i32 s49, 0, 0x1c000
	v_add_u32_e32 v164, s48, v147
	v_add_u32_e32 v180, s49, v147
	ds_read_b128 v[152:155], v164
	ds_read_b128 v[156:159], v164 offset:1024
	ds_read_b128 v[160:163], v164 offset:2048
	ds_read_b128 v[164:167], v164 offset:3072
	ds_read_b128 v[168:171], v180
	ds_read_b128 v[172:175], v180 offset:1024
	ds_read_b128 v[176:179], v180 offset:2048
	ds_read_b128 v[180:183], v180 offset:3072
	s_add_u32 s24, s24, 0x40000
	s_addc_u32 s25, s25, 0
	s_mov_b32 m0, s30
	v_lshl_add_u64 v[226:227], s[24:25], 0, v[134:135]
	ds_read_b128 v[184:187], v151 offset:32768
	ds_read_b128 v[188:191], v151 offset:33792
	ds_read_b128 v[192:195], v151 offset:34816
	ds_read_b128 v[196:199], v151 offset:35840
	ds_read_b128 v[200:203], v151 offset:36864
	ds_read_b128 v[204:207], v151 offset:37888
	ds_read_b128 v[212:215], v151 offset:38912
	ds_read_b128 v[216:219], v151 offset:39936
	global_load_lds_dwordx4 v[226:227], off
	v_lshl_add_u64 v[226:227], s[24:25], 0, v[130:131]
	s_mov_b32 m0, s31
	s_nop 0
	global_load_lds_dwordx4 v[226:227], off
	s_waitcnt vmcnt(8)
	s_waitcnt lgkmcnt(0)
	s_barrier
	s_setprio 1
	s_waitcnt lgkmcnt(0)
	v_mfma_f32_16x16x32_bf16 v[124:127], v[152:155], v[184:187], v[124:127]
	v_mfma_f32_16x16x32_bf16 v[120:123], v[160:163], v[184:187], v[120:123]
	v_mfma_f32_16x16x32_bf16 v[116:119], v[152:155], v[192:195], v[116:119]
	v_mfma_f32_16x16x32_bf16 v[108:111], v[160:163], v[192:195], v[108:111]
	v_mfma_f32_16x16x32_bf16 v[100:103], v[152:155], v[200:203], v[100:103]
	v_mfma_f32_16x16x32_bf16 v[92:95], v[160:163], v[200:203], v[92:95]
	v_mfma_f32_16x16x32_bf16 v[84:87], v[152:155], v[212:215], v[84:87]
	v_mfma_f32_16x16x32_bf16 v[76:79], v[160:163], v[212:215], v[76:79]
	v_mfma_f32_16x16x32_bf16 v[124:127], v[156:159], v[188:191], v[124:127]
	v_mfma_f32_16x16x32_bf16 v[120:123], v[164:167], v[188:191], v[120:123]
	v_mfma_f32_16x16x32_bf16 v[116:119], v[156:159], v[196:199], v[116:119]
	v_mfma_f32_16x16x32_bf16 v[108:111], v[164:167], v[196:199], v[108:111]
	v_mfma_f32_16x16x32_bf16 v[100:103], v[156:159], v[204:207], v[100:103]
	v_mfma_f32_16x16x32_bf16 v[92:95], v[164:167], v[204:207], v[92:95]
	v_mfma_f32_16x16x32_bf16 v[84:87], v[156:159], v[216:219], v[84:87]
	v_mfma_f32_16x16x32_bf16 v[76:79], v[164:167], v[216:219], v[76:79]
	s_setprio 0
	s_setprio 1
	v_mfma_f32_16x16x32_bf16 v[112:115], v[168:171], v[184:187], v[112:115]
	v_mfma_f32_16x16x32_bf16 v[104:107], v[176:179], v[184:187], v[104:107]
	v_mfma_f32_16x16x32_bf16 v[96:99], v[168:171], v[192:195], v[96:99]
	v_mfma_f32_16x16x32_bf16 v[88:91], v[176:179], v[192:195], v[88:91]
	v_mfma_f32_16x16x32_bf16 v[80:83], v[168:171], v[200:203], v[80:83]
	v_mfma_f32_16x16x32_bf16 v[72:75], v[176:179], v[200:203], v[72:75]
	v_mfma_f32_16x16x32_bf16 v[68:71], v[168:171], v[212:215], v[68:71]
	v_mfma_f32_16x16x32_bf16 v[64:67], v[176:179], v[212:215], v[64:67]
	v_mfma_f32_16x16x32_bf16 v[112:115], v[172:175], v[188:191], v[112:115]
	v_mfma_f32_16x16x32_bf16 v[104:107], v[180:183], v[188:191], v[104:107]
	v_mfma_f32_16x16x32_bf16 v[96:99], v[172:175], v[196:199], v[96:99]
	v_mfma_f32_16x16x32_bf16 v[88:91], v[180:183], v[196:199], v[88:91]
	v_mfma_f32_16x16x32_bf16 v[80:83], v[172:175], v[204:207], v[80:83]
	v_mfma_f32_16x16x32_bf16 v[72:75], v[180:183], v[204:207], v[72:75]
	v_mfma_f32_16x16x32_bf16 v[68:71], v[172:175], v[216:219], v[68:71]
	v_mfma_f32_16x16x32_bf16 v[64:67], v[180:183], v[216:219], v[64:67]
	s_setprio 0
	s_barrier
; #define PG8_STAGE(bufoff, gbase, voff) do { _Pragma("unroll") for (int _i = 0; _i < 2; ++_i) \
;         __builtin_amdgcn_global_load_lds((const unsigned*)((const char*)(gbase) + (voff)[_i]), (PG8_LAS unsigned*)(lds + (bufoff) + ldsw + _i * 8192), 16, 0, 0); } while (0)
; #define PG8_LDA(dst, b, h) do { _Pragma("unroll") for (int m = 0; m < 4; ++m) _Pragma("unroll") for (int k = 0; k < 2; ++k) dst[m][k] = *(const PG8_LAS bf16x8*)(lds + PG8_SA(b, h) + aoff + m * 2048 + k * 1024); } while (0)
; #define PG8_MMA(ai, bj, At, Bt) do { __builtin_amdgcn_s_setprio(1); _Pragma("unroll") for (int m = 0; m < 4; ++m) _Pragma("unroll") for (int n = 0; n < 2; ++n) _Pragma("unroll") for (int k = 0; k < 2; ++k) \
;         acc[ai][bj][m][n] = __builtin_amdgcn_mfma_f32_16x16x32_bf16(Bt[n][k], At[m][k], acc[ai][bj][m][n], 0, 0, 0); __builtin_amdgcn_s_setprio(0); } while (0)
; #define PG8_WAIT_V(n) asm volatile("s_waitcnt vmcnt(" #n ")" ::: "memory")
; #define PG8_WAIT_L(n) asm volatile("s_waitcnt lgkmcnt(" #n ")" ::: "memory")
; #define PG8_BAR __builtin_amdgcn_s_barrier()
; #define PG8_SCHED __builtin_amdgcn_sched_barrier(0)
; template <class Epi, class Sched, bool ALIGN_EPI = false, bool SP2 = false>
; __device__ __forceinline__ void gemm_phase(PG8_LAS unsigned char* lds, const Gemm g, const Sched& S, const Epi& E, const int wid) {
;     ...
;         for (int t = 0; t < nt; t += 2) {
;     ...
;             PG8_LDA(At, 1, 1); PG8_STAGE(PG8_SB(1, 0), b3, voffB); PG8_STAGE(PG8_SB(1, 1), b3 + hstep, voffB); PG8_STAGE(PG8_SA(1, 0), a3, voffA);
;             PG8_WAIT_V(8); PG8_WAIT_L(0); PG8_BAR; PG8_MMA(1, 0, At, B0); PG8_MMA(1, 1, At, B1); PG8_BAR; PG8_SCHED;
	s_add_i32 s24, s48, s26
	v_lshl_add_u64 v[144:145], v[144:145], 0, s[6:7]
	s_mov_b32 m0, s24
	ds_read_b128 v[184:187], v151 offset:49152
	ds_read_b128 v[188:191], v151 offset:50176
	ds_read_b128 v[192:195], v151 offset:51200
	ds_read_b128 v[196:199], v151 offset:52224
	ds_read_b128 v[200:203], v151 offset:53248
	ds_read_b128 v[204:207], v151 offset:54272
	ds_read_b128 v[212:215], v151 offset:55296
	ds_read_b128 v[216:219], v151 offset:56320
	global_load_lds_dwordx4 v[144:145], off
	s_add_i32 m0, s24, 0x2000
	s_add_u32 s22, s22, 0x40080
	v_lshl_add_u64 v[144:145], v[220:221], 0, s[6:7]
	s_addc_u32 s23, s23, 0
	s_add_i32 s24, s49, s26
	global_load_lds_dwordx4 v[144:145], off
	v_lshl_add_u64 v[144:145], s[22:23], 0, v[132:133]
	s_mov_b32 m0, s24
	s_nop 0
	global_load_lds_dwordx4 v[144:145], off
	v_lshl_add_u64 v[144:145], s[22:23], 0, v[128:129]
	s_add_i32 m0, s24, 0x2000
	s_nop 0
	global_load_lds_dwordx4 v[144:145], off
	v_lshl_add_u64 v[144:145], v[222:223], 0, s[6:7]
	s_mov_b32 m0, s37
	s_nop 0
	global_load_lds_dwordx4 v[144:145], off
	v_lshl_add_u64 v[144:145], v[224:225], 0, s[6:7]
	s_mov_b32 m0, s38
	s_nop 0
	global_load_lds_dwordx4 v[144:145], off
	s_waitcnt vmcnt(8)
	s_waitcnt lgkmcnt(0)
	s_barrier
	s_setprio 1
	s_waitcnt lgkmcnt(0)
	v_mfma_f32_16x16x32_bf16 v[60:63], v[152:155], v[184:187], v[60:63]
	v_mfma_f32_16x16x32_bf16 v[56:59], v[160:163], v[184:187], v[56:59]
	v_mfma_f32_16x16x32_bf16 v[52:55], v[152:155], v[192:195], v[52:55]
	v_mfma_f32_16x16x32_bf16 v[44:47], v[160:163], v[192:195], v[44:47]
	v_mfma_f32_16x16x32_bf16 v[36:39], v[152:155], v[200:203], v[36:39]
	v_mfma_f32_16x16x32_bf16 v[28:31], v[160:163], v[200:203], v[28:31]
	v_mfma_f32_16x16x32_bf16 v[20:23], v[152:155], v[212:215], v[20:23]
	v_mfma_f32_16x16x32_bf16 v[12:15], v[160:163], v[212:215], v[12:15]
	v_mfma_f32_16x16x32_bf16 v[60:63], v[156:159], v[188:191], v[60:63]
	v_mfma_f32_16x16x32_bf16 v[56:59], v[164:167], v[188:191], v[56:59]
	v_mfma_f32_16x16x32_bf16 v[52:55], v[156:159], v[196:199], v[52:55]
	v_mfma_f32_16x16x32_bf16 v[44:47], v[164:167], v[196:199], v[44:47]
	v_mfma_f32_16x16x32_bf16 v[36:39], v[156:159], v[204:207], v[36:39]
	v_mfma_f32_16x16x32_bf16 v[28:31], v[164:167], v[204:207], v[28:31]
	v_mfma_f32_16x16x32_bf16 v[20:23], v[156:159], v[216:219], v[20:23]
	v_mfma_f32_16x16x32_bf16 v[12:15], v[164:167], v[216:219], v[12:15]
	s_setprio 0
	s_setprio 1
	v_mfma_f32_16x16x32_bf16 v[48:51], v[168:171], v[184:187], v[48:51]
	v_mfma_f32_16x16x32_bf16 v[40:43], v[176:179], v[184:187], v[40:43]
	v_mfma_f32_16x16x32_bf16 v[32:35], v[168:171], v[192:195], v[32:35]
	v_mfma_f32_16x16x32_bf16 v[24:27], v[176:179], v[192:195], v[24:27]
	v_mfma_f32_16x16x32_bf16 v[16:19], v[168:171], v[200:203], v[16:19]
	v_mfma_f32_16x16x32_bf16 v[8:11], v[176:179], v[200:203], v[8:11]
	v_mfma_f32_16x16x32_bf16 v[4:7], v[168:171], v[212:215], v[4:7]
	v_mfma_f32_16x16x32_bf16 v[0:3], v[176:179], v[212:215], v[0:3]
	v_mfma_f32_16x16x32_bf16 v[48:51], v[172:175], v[188:191], v[48:51]
	v_mfma_f32_16x16x32_bf16 v[40:43], v[180:183], v[188:191], v[40:43]
	v_mfma_f32_16x16x32_bf16 v[32:35], v[172:175], v[196:199], v[32:35]
	v_mfma_f32_16x16x32_bf16 v[24:27], v[180:183], v[196:199], v[24:27]
	v_mfma_f32_16x16x32_bf16 v[16:19], v[172:175], v[204:207], v[16:19]
	v_mfma_f32_16x16x32_bf16 v[8:11], v[180:183], v[204:207], v[8:11]
	v_mfma_f32_16x16x32_bf16 v[4:7], v[172:175], v[216:219], v[4:7]
	v_mfma_f32_16x16x32_bf16 v[0:3], v[180:183], v[216:219], v[0:3]
	s_setprio 0
	s_barrier
	s_add_i32 s47, s47, 2
	s_add_u32 s20, s20, 0x100
	s_addc_u32 s21, s21, 0
	s_add_u32 s45, s45, 0x100
	s_addc_u32 s46, s46, 0
	s_cmp_gt_u32 s47, 13
	s_cbranch_scc0 .LBB0_882
	s_branch .Lkp_exit_2

; template <class Epi, class Sched, bool ALIGN_EPI = false, bool SP2 = false>
; __device__ __forceinline__ void gemm_phase(PG8_LAS unsigned char* lds, const Gemm g, const Sched& S, const Epi& E, const int wid) {
;     ...
;         const bool has_next = S.next(ui + 1, nxt);
;         const char* nA = has_next ? (const char*)g.A + (size_t)nxt.pm * tstep : cA; const char* nB = has_next ? (const char*)g.Bt + (size_t)nxt.pn * tstep : cB;
;         for (int t = 0; t < nt; t += 2) {
;             const bool last = (t == nt - 2);
;             const char* a1 = cA + (size_t)(t + 1) * kstep;
;             const char* a2 = last ? nA : cA + (size_t)(t + 2) * kstep; const char* b2 = last ? nB : cB + (size_t)(t + 2) * kstep;
;             const char* a3 = a2 + kstep; const char* b3 = b2 + kstep;
.LBB0_1911:
	s_ashr_i32 s15, s14, 31
	s_lshl_b64 s[16:17], s[14:15], 19
	s_add_u32 s16, s80, s16
	s_addc_u32 s17, s81, s17
	s_and_b64 s[18:19], s[4:5], exec
	s_cselect_b32 s15, s17, s23
	s_cselect_b32 s42, s16, s22
	s_ashr_i32 s13, s12, 31
	s_lshl_b64 s[18:19], s[12:13], 19
	s_add_u32 s18, s10, s18
	s_addc_u32 s19, s11, s19
	s_and_b64 s[26:27], s[4:5], exec
	s_cselect_b32 s13, s19, s25
	s_cselect_b32 s43, s18, s24
	s_add_u32 s22, s22, 0x40080
	s_addc_u32 s23, s23, 0
	s_add_u32 s44, s24, 0x100

; template <class Epi, class Sched, bool ALIGN_EPI = false, bool SP2 = false>
; __device__ __forceinline__ void gemm_phase(PG8_LAS unsigned char* lds, const Gemm g, const Sched& S, const Epi& E, const int wid) {
;     ...
; #pragma unroll
;         for (int a = 0; a < 2; ++a)
; #pragma unroll
;             for (int b = 0; b < 2; ++b)
; #pragma unroll
;                 for (int m = 0; m < 4; ++m)
; #pragma unroll
;                     for (int n = 0; n < 2; ++n) acc[a][b][m][n] = (f32x4){0.f, 0.f, 0.f, 0.f};
	s_addc_u32 s45, s25, 0
	s_mov_b32 s46, -2


; #define PG8_STAGE(bufoff, gbase, voff) do { _Pragma("unroll") for (int _i = 0; _i < 2; ++_i) \
;         __builtin_amdgcn_global_load_lds((const unsigned*)((const char*)(gbase) + (voff)[_i]), (PG8_LAS unsigned*)(lds + (bufoff) + ldsw + _i * 8192), 16, 0, 0); } while (0)
; #define PG8_LDA(dst, b, h) do { _Pragma("unroll") for (int m = 0; m < 4; ++m) _Pragma("unroll") for (int k = 0; k < 2; ++k) dst[m][k] = *(const PG8_LAS bf16x8*)(lds + PG8_SA(b, h) + aoff + m * 2048 + k * 1024); } while (0)
; #define PG8_LDB(dst, b, h) do { _Pragma("unroll") for (int n = 0; n < 2; ++n) _Pragma("unroll") for (int k = 0; k < 2; ++k) dst[n][k] = *(const PG8_LAS bf16x8*)(lds + PG8_SB(b, h) + boff + n * 2048 + k * 1024); } while (0)
; #define PG8_MMA(ai, bj, At, Bt) do { __builtin_amdgcn_s_setprio(1); _Pragma("unroll") for (int m = 0; m < 4; ++m) _Pragma("unroll") for (int n = 0; n < 2; ++n) _Pragma("unroll") for (int k = 0; k < 2; ++k) \
;         acc[ai][bj][m][n] = __builtin_amdgcn_mfma_f32_16x16x32_bf16(Bt[n][k], At[m][k], acc[ai][bj][m][n], 0, 0, 0); __builtin_amdgcn_s_setprio(0); } while (0)
; #define PG8_WAIT_V(n) asm volatile("s_waitcnt vmcnt(" #n ")" ::: "memory")
; #define PG8_WAIT_L(n) asm volatile("s_waitcnt lgkmcnt(" #n ")" ::: "memory")
; #define PG8_BAR __builtin_amdgcn_s_barrier()
; #define PG8_SCHED __builtin_amdgcn_sched_barrier(0)
; template <class Epi, class Sched, bool ALIGN_EPI = false, bool SP2 = false>
; __device__ __forceinline__ void gemm_phase(PG8_LAS unsigned char* lds, const Gemm g, const Sched& S, const Epi& E, const int wid) {
;     ...
;             PG8_LDB(B0, 0, 0); PG8_LDB(B1, 0, 1); PG8_SCHED; PG8_LDA(At, 0, 0); PG8_STAGE(PG8_SA(1, 1), a1 + hstep, voffA);
;             PG8_WAIT_V(8); PG8_WAIT_L(0); PG8_BAR; PG8_MMA(0, 0, At, B0); PG8_MMA(0, 1, At, B1); PG8_BAR; PG8_SCHED;
;             PG8_LDA(At, 0, 1); PG8_STAGE(PG8_SB(0, 0), b2, voffB); PG8_STAGE(PG8_SB(0, 1), b2 + hstep, voffB); PG8_STAGE(PG8_SA(0, 0), a2, voffA);
;             PG8_WAIT_V(8); PG8_WAIT_L(0); PG8_BAR; PG8_MMA(1, 0, At, B0); PG8_MMA(1, 1, At, B1); PG8_BAR; PG8_SCHED;
	ds_read_b128 v[144:147], v151
	ds_read_b128 v[154:157], v151 offset:1024
	ds_read_b128 v[158:161], v151 offset:2048
	ds_read_b128 v[162:165], v151 offset:3072
	ds_read_b128 v[166:169], v152
	ds_read_b128 v[170:173], v152 offset:1024
	ds_read_b128 v[174:177], v152 offset:2048
	ds_read_b128 v[178:181], v152 offset:3072
	s_add_u32 s24, s22, 0xfffc0080
	s_addc_u32 s25, s23, -1
	s_cmp_eq_u32 s46, 12
	s_cselect_b32 s27, s15, s25
	s_cselect_b32 s26, s42, s24
	s_cselect_b32 s25, s13, s45
	s_cselect_b32 s24, s43, s44
	v_lshl_add_u64 v[206:207], s[22:23], 0, v[136:137]
	s_add_i32 m0, s21, 0xc000
	ds_read_b128 v[182:185], v153
	ds_read_b128 v[186:189], v153 offset:1024
	ds_read_b128 v[190:193], v153 offset:2048
	ds_read_b128 v[194:197], v153 offset:3072
	ds_read_b128 v[198:201], v153 offset:4096
	ds_read_b128 v[202:205], v153 offset:5120
	ds_read_b128 v[210:213], v153 offset:6144
	ds_read_b128 v[214:217], v153 offset:7168
	global_load_lds_dwordx4 v[206:207], off
	v_lshl_add_u64 v[206:207], s[22:23], 0, v[138:139]
	s_add_i32 m0, s21, 0xe000
	s_nop 0
	global_load_lds_dwordx4 v[206:207], off
	s_waitcnt vmcnt(8)
	s_waitcnt lgkmcnt(0)
	s_barrier
	s_setprio 1
	s_waitcnt lgkmcnt(0)
	v_mfma_f32_16x16x32_bf16 v[124:127], v[144:147], v[182:185], 0
	v_mfma_f32_16x16x32_bf16 v[116:119], v[158:161], v[182:185], 0
	v_mfma_f32_16x16x32_bf16 v[108:111], v[144:147], v[190:193], 0
	v_mfma_f32_16x16x32_bf16 v[100:103], v[158:161], v[190:193], 0
	v_mfma_f32_16x16x32_bf16 v[92:95], v[144:147], v[198:201], 0
	v_mfma_f32_16x16x32_bf16 v[84:87], v[158:161], v[198:201], 0
	v_mfma_f32_16x16x32_bf16 v[76:79], v[144:147], v[210:213], 0
	v_mfma_f32_16x16x32_bf16 v[68:71], v[158:161], v[210:213], 0
	v_mfma_f32_16x16x32_bf16 v[124:127], v[154:157], v[186:189], v[124:127]
	v_mfma_f32_16x16x32_bf16 v[116:119], v[162:165], v[186:189], v[116:119]
	v_mfma_f32_16x16x32_bf16 v[108:111], v[154:157], v[194:197], v[108:111]
	v_mfma_f32_16x16x32_bf16 v[100:103], v[162:165], v[194:197], v[100:103]
	v_mfma_f32_16x16x32_bf16 v[92:95], v[154:157], v[202:205], v[92:95]
	v_mfma_f32_16x16x32_bf16 v[84:87], v[162:165], v[202:205], v[84:87]
	v_mfma_f32_16x16x32_bf16 v[76:79], v[154:157], v[214:217], v[76:79]
	v_mfma_f32_16x16x32_bf16 v[68:71], v[162:165], v[214:217], v[68:71]
	s_setprio 0
	s_setprio 1
	v_mfma_f32_16x16x32_bf16 v[120:123], v[166:169], v[182:185], 0
	v_mfma_f32_16x16x32_bf16 v[112:115], v[174:177], v[182:185], 0
	v_mfma_f32_16x16x32_bf16 v[104:107], v[166:169], v[190:193], 0
	v_mfma_f32_16x16x32_bf16 v[96:99], v[174:177], v[190:193], 0
	v_mfma_f32_16x16x32_bf16 v[88:91], v[166:169], v[198:201], 0
	v_mfma_f32_16x16x32_bf16 v[80:83], v[174:177], v[198:201], 0
	v_mfma_f32_16x16x32_bf16 v[72:75], v[166:169], v[210:213], 0
	v_mfma_f32_16x16x32_bf16 v[64:67], v[174:177], v[210:213], 0
	v_mfma_f32_16x16x32_bf16 v[120:123], v[170:173], v[186:189], v[120:123]
	v_mfma_f32_16x16x32_bf16 v[112:115], v[178:181], v[186:189], v[112:115]
	v_mfma_f32_16x16x32_bf16 v[104:107], v[170:173], v[194:197], v[104:107]
	v_mfma_f32_16x16x32_bf16 v[96:99], v[178:181], v[194:197], v[96:99]
	v_mfma_f32_16x16x32_bf16 v[88:91], v[170:173], v[202:205], v[88:91]
	v_mfma_f32_16x16x32_bf16 v[80:83], v[178:181], v[202:205], v[80:83]
	v_mfma_f32_16x16x32_bf16 v[72:75], v[170:173], v[214:217], v[72:75]
	v_mfma_f32_16x16x32_bf16 v[64:67], v[178:181], v[214:217], v[64:67]
	s_setprio 0
	s_barrier
	s_add_i32 s47, s38, s9
	v_lshl_add_u64 v[206:207], s[24:25], 0, v[132:133]
	s_mov_b32 m0, s47
	ds_read_b128 v[182:185], v153 offset:16384
	ds_read_b128 v[186:189], v153 offset:17408
	ds_read_b128 v[190:193], v153 offset:18432
	ds_read_b128 v[194:197], v153 offset:19456
	ds_read_b128 v[198:201], v153 offset:20480
	ds_read_b128 v[202:205], v153 offset:21504
	ds_read_b128 v[210:213], v153 offset:22528
	ds_read_b128 v[214:217], v153 offset:23552
	global_load_lds_dwordx4 v[206:207], off
	s_add_i32 m0, s47, 0x2000
	s_add_u32 s48, s24, 0x40000
	v_lshl_add_u64 v[218:219], s[24:25], 0, v[128:129]
	s_addc_u32 s49, s25, 0
	s_add_i32 s47, s39, s9
	global_load_lds_dwordx4 v[218:219], off
	v_lshl_add_u64 v[220:221], s[48:49], 0, v[132:133]
	s_mov_b32 m0, s47
	v_lshl_add_u64 v[222:223], s[26:27], 0, v[130:131]
	global_load_lds_dwordx4 v[220:221], off
	v_lshl_add_u64 v[220:221], s[48:49], 0, v[128:129]
	s_add_i32 m0, s47, 0x2000
	s_nop 0
	global_load_lds_dwordx4 v[220:221], off
	v_lshl_add_u64 v[220:221], s[26:27], 0, v[134:135]
	s_mov_b32 m0, s21
	s_nop 0
	global_load_lds_dwordx4 v[220:221], off
	s_mov_b32 m0, s30
	s_nop 0
	global_load_lds_dwordx4 v[222:223], off
	s_waitcnt vmcnt(8)
	s_waitcnt lgkmcnt(0)
	s_barrier
; #define PG8_STAGE(bufoff, gbase, voff) do { _Pragma("unroll") for (int _i = 0; _i < 2; ++_i) \
;         __builtin_amdgcn_global_load_lds((const unsigned*)((const char*)(gbase) + (voff)[_i]), (PG8_LAS unsigned*)(lds + (bufoff) + ldsw + _i * 8192), 16, 0, 0); } while (0)
; #define PG8_LDA(dst, b, h) do { _Pragma("unroll") for (int m = 0; m < 4; ++m) _Pragma("unroll") for (int k = 0; k < 2; ++k) dst[m][k] = *(const PG8_LAS bf16x8*)(lds + PG8_SA(b, h) + aoff + m * 2048 + k * 1024); } while (0)
; #define PG8_LDB(dst, b, h) do { _Pragma("unroll") for (int n = 0; n < 2; ++n) _Pragma("unroll") for (int k = 0; k < 2; ++k) dst[n][k] = *(const PG8_LAS bf16x8*)(lds + PG8_SB(b, h) + boff + n * 2048 + k * 1024); } while (0)
; #define PG8_MMA(ai, bj, At, Bt) do { __builtin_amdgcn_s_setprio(1); _Pragma("unroll") for (int m = 0; m < 4; ++m) _Pragma("unroll") for (int n = 0; n < 2; ++n) _Pragma("unroll") for (int k = 0; k < 2; ++k) \
;         acc[ai][bj][m][n] = __builtin_amdgcn_mfma_f32_16x16x32_bf16(Bt[n][k], At[m][k], acc[ai][bj][m][n], 0, 0, 0); __builtin_amdgcn_s_setprio(0); } while (0)
; #define PG8_WAIT_V(n) asm volatile("s_waitcnt vmcnt(" #n ")" ::: "memory")
; #define PG8_WAIT_L(n) asm volatile("s_waitcnt lgkmcnt(" #n ")" ::: "memory")
; #define PG8_BAR __builtin_amdgcn_s_barrier()
; #define PG8_SCHED __builtin_amdgcn_sched_barrier(0)
; template <class Epi, class Sched, bool ALIGN_EPI = false, bool SP2 = false>
; __device__ __forceinline__ void gemm_phase(PG8_LAS unsigned char* lds, const Gemm g, const Sched& S, const Epi& E, const int wid) {
;     ...
;             PG8_WAIT_V(8); PG8_WAIT_L(0); PG8_BAR; PG8_MMA(1, 0, At, B0); PG8_MMA(1, 1, At, B1); PG8_BAR; PG8_SCHED;
;             PG8_LDB(B0, 1, 0); PG8_LDB(B1, 1, 1); PG8_SCHED; PG8_LDA(At, 1, 0); PG8_STAGE(PG8_SA(0, 1), a2 + hstep, voffA);
;             PG8_WAIT_V(8); PG8_WAIT_L(0); PG8_BAR; PG8_MMA(0, 0, At, B0); PG8_MMA(0, 1, At, B1); PG8_BAR; PG8_SCHED;
	s_setprio 1
	s_waitcnt lgkmcnt(0)
	v_mfma_f32_16x16x32_bf16 v[60:63], v[144:147], v[182:185], 0
	v_mfma_f32_16x16x32_bf16 v[52:55], v[158:161], v[182:185], 0
	v_mfma_f32_16x16x32_bf16 v[44:47], v[144:147], v[190:193], 0
	v_mfma_f32_16x16x32_bf16 v[36:39], v[158:161], v[190:193], 0
	v_mfma_f32_16x16x32_bf16 v[28:31], v[144:147], v[198:201], 0
	v_mfma_f32_16x16x32_bf16 v[20:23], v[158:161], v[198:201], 0
	v_mfma_f32_16x16x32_bf16 v[12:15], v[144:147], v[210:213], 0
	v_mfma_f32_16x16x32_bf16 v[4:7], v[158:161], v[210:213], 0
	v_mfma_f32_16x16x32_bf16 v[60:63], v[154:157], v[186:189], v[60:63]
	v_mfma_f32_16x16x32_bf16 v[52:55], v[162:165], v[186:189], v[52:55]
	v_mfma_f32_16x16x32_bf16 v[44:47], v[154:157], v[194:197], v[44:47]
	v_mfma_f32_16x16x32_bf16 v[36:39], v[162:165], v[194:197], v[36:39]
	v_mfma_f32_16x16x32_bf16 v[28:31], v[154:157], v[202:205], v[28:31]
	v_mfma_f32_16x16x32_bf16 v[20:23], v[162:165], v[202:205], v[20:23]
	v_mfma_f32_16x16x32_bf16 v[12:15], v[154:157], v[214:217], v[12:15]
	v_mfma_f32_16x16x32_bf16 v[4:7], v[162:165], v[214:217], v[4:7]
	s_setprio 0
	s_setprio 1
	v_mfma_f32_16x16x32_bf16 v[56:59], v[166:169], v[182:185], 0
	v_mfma_f32_16x16x32_bf16 v[48:51], v[174:177], v[182:185], 0
	v_mfma_f32_16x16x32_bf16 v[40:43], v[166:169], v[190:193], 0
	v_mfma_f32_16x16x32_bf16 v[32:35], v[174:177], v[190:193], 0
	v_mfma_f32_16x16x32_bf16 v[24:27], v[166:169], v[198:201], 0
	v_mfma_f32_16x16x32_bf16 v[16:19], v[174:177], v[198:201], 0
	v_mfma_f32_16x16x32_bf16 v[8:11], v[166:169], v[210:213], 0
	v_mfma_f32_16x16x32_bf16 v[0:3], v[174:177], v[210:213], 0
	v_mfma_f32_16x16x32_bf16 v[56:59], v[170:173], v[186:189], v[56:59]
	v_mfma_f32_16x16x32_bf16 v[48:51], v[178:181], v[186:189], v[48:51]
	v_mfma_f32_16x16x32_bf16 v[40:43], v[170:173], v[194:197], v[40:43]
	v_mfma_f32_16x16x32_bf16 v[32:35], v[178:181], v[194:197], v[32:35]
	v_mfma_f32_16x16x32_bf16 v[24:27], v[170:173], v[202:205], v[24:27]
	v_mfma_f32_16x16x32_bf16 v[16:19], v[178:181], v[202:205], v[16:19]
	v_mfma_f32_16x16x32_bf16 v[8:11], v[170:173], v[214:217], v[8:11]
	v_mfma_f32_16x16x32_bf16 v[0:3], v[178:181], v[214:217], v[0:3]
	s_setprio 0
	s_barrier
	s_add_i32 s47, 0, 0x18000
	s_add_i32 s48, 0, 0x1c000
	v_add_u32_e32 v162, s47, v149
	v_add_u32_e32 v178, s48, v149
	ds_read_b128 v[144:147], v162
	ds_read_b128 v[154:157], v162 offset:1024
	ds_read_b128 v[158:161], v162 offset:2048
	ds_read_b128 v[162:165], v162 offset:3072
	ds_read_b128 v[166:169], v178
	ds_read_b128 v[170:173], v178 offset:1024
	ds_read_b128 v[174:177], v178 offset:2048
	ds_read_b128 v[178:181], v178 offset:3072
	s_add_u32 s26, s26, 0x40000
	s_addc_u32 s27, s27, 0
	s_mov_b32 m0, s31
	v_lshl_add_u64 v[224:225], s[26:27], 0, v[134:135]
	ds_read_b128 v[182:185], v153 offset:32768
	ds_read_b128 v[186:189], v153 offset:33792
	ds_read_b128 v[190:193], v153 offset:34816
	ds_read_b128 v[194:197], v153 offset:35840
	ds_read_b128 v[198:201], v153 offset:36864
	ds_read_b128 v[202:205], v153 offset:37888
	ds_read_b128 v[210:213], v153 offset:38912
	ds_read_b128 v[214:217], v153 offset:39936
	global_load_lds_dwordx4 v[224:225], off
	v_lshl_add_u64 v[224:225], s[26:27], 0, v[130:131]
	s_mov_b32 m0, s33
	s_nop 0
	global_load_lds_dwordx4 v[224:225], off
	s_waitcnt vmcnt(8)
	s_waitcnt lgkmcnt(0)
	s_barrier
	s_setprio 1
	s_waitcnt lgkmcnt(0)
	v_mfma_f32_16x16x32_bf16 v[124:127], v[144:147], v[182:185], v[124:127]
	v_mfma_f32_16x16x32_bf16 v[116:119], v[158:161], v[182:185], v[116:119]
	v_mfma_f32_16x16x32_bf16 v[108:111], v[144:147], v[190:193], v[108:111]
	v_mfma_f32_16x16x32_bf16 v[100:103], v[158:161], v[190:193], v[100:103]
	v_mfma_f32_16x16x32_bf16 v[92:95], v[144:147], v[198:201], v[92:95]
	v_mfma_f32_16x16x32_bf16 v[84:87], v[158:161], v[198:201], v[84:87]
	v_mfma_f32_16x16x32_bf16 v[76:79], v[144:147], v[210:213], v[76:79]
	v_mfma_f32_16x16x32_bf16 v[68:71], v[158:161], v[210:213], v[68:71]
	v_mfma_f32_16x16x32_bf16 v[124:127], v[154:157], v[186:189], v[124:127]
	v_mfma_f32_16x16x32_bf16 v[116:119], v[162:165], v[186:189], v[116:119]
	v_mfma_f32_16x16x32_bf16 v[108:111], v[154:157], v[194:197], v[108:111]
	v_mfma_f32_16x16x32_bf16 v[100:103], v[162:165], v[194:197], v[100:103]
	v_mfma_f32_16x16x32_bf16 v[92:95], v[154:157], v[202:205], v[92:95]
	v_mfma_f32_16x16x32_bf16 v[84:87], v[162:165], v[202:205], v[84:87]
	v_mfma_f32_16x16x32_bf16 v[76:79], v[154:157], v[214:217], v[76:79]
	v_mfma_f32_16x16x32_bf16 v[68:71], v[162:165], v[214:217], v[68:71]
	s_setprio 0
	s_setprio 1
	v_mfma_f32_16x16x32_bf16 v[120:123], v[166:169], v[182:185], v[120:123]
	v_mfma_f32_16x16x32_bf16 v[112:115], v[174:177], v[182:185], v[112:115]
	v_mfma_f32_16x16x32_bf16 v[104:107], v[166:169], v[190:193], v[104:107]
	v_mfma_f32_16x16x32_bf16 v[96:99], v[174:177], v[190:193], v[96:99]
	v_mfma_f32_16x16x32_bf16 v[88:91], v[166:169], v[198:201], v[88:91]
	v_mfma_f32_16x16x32_bf16 v[80:83], v[174:177], v[198:201], v[80:83]
	v_mfma_f32_16x16x32_bf16 v[72:75], v[166:169], v[210:213], v[72:75]
	v_mfma_f32_16x16x32_bf16 v[64:67], v[174:177], v[210:213], v[64:67]
	v_mfma_f32_16x16x32_bf16 v[120:123], v[170:173], v[186:189], v[120:123]
	v_mfma_f32_16x16x32_bf16 v[112:115], v[178:181], v[186:189], v[112:115]
	v_mfma_f32_16x16x32_bf16 v[104:107], v[170:173], v[194:197], v[104:107]
	v_mfma_f32_16x16x32_bf16 v[96:99], v[178:181], v[194:197], v[96:99]
	v_mfma_f32_16x16x32_bf16 v[88:91], v[170:173], v[202:205], v[88:91]
	v_mfma_f32_16x16x32_bf16 v[80:83], v[178:181], v[202:205], v[80:83]
	v_mfma_f32_16x16x32_bf16 v[72:75], v[170:173], v[214:217], v[72:75]
	v_mfma_f32_16x16x32_bf16 v[64:67], v[178:181], v[214:217], v[64:67]
	s_setprio 0
	s_barrier
; #define PG8_STAGE(bufoff, gbase, voff) do { _Pragma("unroll") for (int _i = 0; _i < 2; ++_i) \
;         __builtin_amdgcn_global_load_lds((const unsigned*)((const char*)(gbase) + (voff)[_i]), (PG8_LAS unsigned*)(lds + (bufoff) + ldsw + _i * 8192), 16, 0, 0); } while (0)
; #define PG8_LDA(dst, b, h) do { _Pragma("unroll") for (int m = 0; m < 4; ++m) _Pragma("unroll") for (int k = 0; k < 2; ++k) dst[m][k] = *(const PG8_LAS bf16x8*)(lds + PG8_SA(b, h) + aoff + m * 2048 + k * 1024); } while (0)
; #define PG8_MMA(ai, bj, At, Bt) do { __builtin_amdgcn_s_setprio(1); _Pragma("unroll") for (int m = 0; m < 4; ++m) _Pragma("unroll") for (int n = 0; n < 2; ++n) _Pragma("unroll") for (int k = 0; k < 2; ++k) \
;         acc[ai][bj][m][n] = __builtin_amdgcn_mfma_f32_16x16x32_bf16(Bt[n][k], At[m][k], acc[ai][bj][m][n], 0, 0, 0); __builtin_amdgcn_s_setprio(0); } while (0)
; #define PG8_WAIT_V(n) asm volatile("s_waitcnt vmcnt(" #n ")" ::: "memory")
; #define PG8_WAIT_L(n) asm volatile("s_waitcnt lgkmcnt(" #n ")" ::: "memory")
; #define PG8_BAR __builtin_amdgcn_s_barrier()
; #define PG8_SCHED __builtin_amdgcn_sched_barrier(0)
; template <class Epi, class Sched, bool ALIGN_EPI = false, bool SP2 = false>
; __device__ __forceinline__ void gemm_phase(PG8_LAS unsigned char* lds, const Gemm g, const Sched& S, const Epi& E, const int wid) {
;     ...
;         for (int t = 0; t < nt; t += 2) {
;     ...
;             PG8_LDA(At, 1, 1); PG8_STAGE(PG8_SB(1, 0), b3, voffB); PG8_STAGE(PG8_SB(1, 1), b3 + hstep, voffB); PG8_STAGE(PG8_SA(1, 0), a3, voffA);
;             PG8_WAIT_V(8); PG8_WAIT_L(0); PG8_BAR; PG8_MMA(1, 0, At, B0); PG8_MMA(1, 1, At, B1); PG8_BAR; PG8_SCHED;
	s_add_i32 s26, s47, s9
	v_lshl_add_u64 v[206:207], v[206:207], 0, s[2:3]
	s_mov_b32 m0, s26
	ds_read_b128 v[182:185], v153 offset:49152
	ds_read_b128 v[186:189], v153 offset:50176
	ds_read_b128 v[190:193], v153 offset:51200
	ds_read_b128 v[194:197], v153 offset:52224
	ds_read_b128 v[198:201], v153 offset:53248
	ds_read_b128 v[202:205], v153 offset:54272
	ds_read_b128 v[210:213], v153 offset:55296
	ds_read_b128 v[214:217], v153 offset:56320
	global_load_lds_dwordx4 v[206:207], off
	s_add_i32 m0, s26, 0x2000
	s_add_u32 s24, s24, 0x40080
	v_lshl_add_u64 v[206:207], v[218:219], 0, s[2:3]
	s_addc_u32 s25, s25, 0
	s_add_i32 s26, s48, s9
	global_load_lds_dwordx4 v[206:207], off
	v_lshl_add_u64 v[206:207], s[24:25], 0, v[132:133]
	s_mov_b32 m0, s26
	s_nop 0
	global_load_lds_dwordx4 v[206:207], off
	v_lshl_add_u64 v[206:207], s[24:25], 0, v[128:129]
	s_add_i32 m0, s26, 0x2000
	s_nop 0
	global_load_lds_dwordx4 v[206:207], off
	v_lshl_add_u64 v[206:207], v[220:221], 0, s[2:3]
	s_mov_b32 m0, s35
	s_nop 0
	global_load_lds_dwordx4 v[206:207], off
	v_lshl_add_u64 v[206:207], v[222:223], 0, s[2:3]
	s_mov_b32 m0, s36
	s_nop 0
	global_load_lds_dwordx4 v[206:207], off
	s_waitcnt vmcnt(8)
	s_waitcnt lgkmcnt(0)
	s_barrier
	s_setprio 1
	s_waitcnt lgkmcnt(0)
	v_mfma_f32_16x16x32_bf16 v[60:63], v[144:147], v[182:185], v[60:63]
	v_mfma_f32_16x16x32_bf16 v[52:55], v[158:161], v[182:185], v[52:55]
	v_mfma_f32_16x16x32_bf16 v[44:47], v[144:147], v[190:193], v[44:47]
	v_mfma_f32_16x16x32_bf16 v[36:39], v[158:161], v[190:193], v[36:39]
	v_mfma_f32_16x16x32_bf16 v[28:31], v[144:147], v[198:201], v[28:31]
	v_mfma_f32_16x16x32_bf16 v[20:23], v[158:161], v[198:201], v[20:23]
	v_mfma_f32_16x16x32_bf16 v[12:15], v[144:147], v[210:213], v[12:15]
	v_mfma_f32_16x16x32_bf16 v[4:7], v[158:161], v[210:213], v[4:7]
	v_mfma_f32_16x16x32_bf16 v[60:63], v[154:157], v[186:189], v[60:63]
	v_mfma_f32_16x16x32_bf16 v[52:55], v[162:165], v[186:189], v[52:55]
	v_mfma_f32_16x16x32_bf16 v[44:47], v[154:157], v[194:197], v[44:47]
	v_mfma_f32_16x16x32_bf16 v[36:39], v[162:165], v[194:197], v[36:39]
	v_mfma_f32_16x16x32_bf16 v[28:31], v[154:157], v[202:205], v[28:31]
	v_mfma_f32_16x16x32_bf16 v[20:23], v[162:165], v[202:205], v[20:23]
	v_mfma_f32_16x16x32_bf16 v[12:15], v[154:157], v[214:217], v[12:15]
	v_mfma_f32_16x16x32_bf16 v[4:7], v[162:165], v[214:217], v[4:7]
	s_setprio 0
	s_setprio 1
	v_mfma_f32_16x16x32_bf16 v[56:59], v[166:169], v[182:185], v[56:59]
	v_mfma_f32_16x16x32_bf16 v[48:51], v[174:177], v[182:185], v[48:51]
	v_mfma_f32_16x16x32_bf16 v[40:43], v[166:169], v[190:193], v[40:43]
	v_mfma_f32_16x16x32_bf16 v[32:35], v[174:177], v[190:193], v[32:35]
	v_mfma_f32_16x16x32_bf16 v[24:27], v[166:169], v[198:201], v[24:27]
	v_mfma_f32_16x16x32_bf16 v[16:19], v[174:177], v[198:201], v[16:19]
	v_mfma_f32_16x16x32_bf16 v[8:11], v[166:169], v[210:213], v[8:11]
	v_mfma_f32_16x16x32_bf16 v[0:3], v[174:177], v[210:213], v[0:3]
	v_mfma_f32_16x16x32_bf16 v[56:59], v[170:173], v[186:189], v[56:59]
	v_mfma_f32_16x16x32_bf16 v[48:51], v[178:181], v[186:189], v[48:51]
	v_mfma_f32_16x16x32_bf16 v[40:43], v[170:173], v[194:197], v[40:43]
	v_mfma_f32_16x16x32_bf16 v[32:35], v[178:181], v[194:197], v[32:35]
	v_mfma_f32_16x16x32_bf16 v[24:27], v[170:173], v[202:205], v[24:27]
	v_mfma_f32_16x16x32_bf16 v[16:19], v[178:181], v[202:205], v[16:19]
	v_mfma_f32_16x16x32_bf16 v[8:11], v[170:173], v[214:217], v[8:11]
	v_mfma_f32_16x16x32_bf16 v[0:3], v[178:181], v[214:217], v[0:3]
	s_setprio 0
	s_barrier
	s_add_i32 s46, s46, 2
	s_add_u32 s22, s22, 0x100
	s_addc_u32 s23, s23, 0
	s_add_u32 s44, s44, 0x100
	s_addc_u32 s45, s45, 0
	s_cmp_gt_u32 s46, 13
	s_cbranch_scc0 .LBB0_1912
	s_branch .Lkp_exit_4

; #define PG8_BAR __builtin_amdgcn_s_barrier()
; template <class Epi, class Sched, bool ALIGN_EPI = false, bool SP2 = false>
; __device__ __forceinline__ void gemm_phase(PG8_LAS unsigned char* lds, const Gemm g, const Sched& S, const Epi& E, const int wid) {
;     ...
;         if constexpr (ALIGN_EPI) { if (wr == 0) PG8_BAR; }
.Lkp_exit_4:
	s_and_b64 vcc, exec, s[6:7]
	s_cbranch_vccz .LBB0_1915
	s_barrier
